# nt cache policy on the once-written FF1 / FF2 GEMM output stores
# baseline (speedup 1.0000x reference)
.LBB0_1492:
	ds_read_b128 v[142:145], v139
	ds_read_b128 v[146:149], v139 offset:1024
	ds_read_b128 v[150:153], v139 offset:2048
	ds_read_b128 v[154:157], v139 offset:3072
	s_add_u32 s0, s28, 0xfff80080
	s_addc_u32 s1, s29, -1
	s_cmp_eq_u32 s55, 28
	s_cselect_b32 s35, s15, s1
	s_cselect_b32 s34, s51, s0
	s_cselect_b32 s31, s17, s54
	s_cselect_b32 s30, s52, s53
	v_lshl_add_u64 v[190:191], s[28:29], 0, v[132:133]
	s_add_i32 m0, s25, 0xc000
	ds_read_b128 v[158:161], v140
	ds_read_b128 v[162:165], v140 offset:1024
	ds_read_b128 v[166:169], v140 offset:2048
	ds_read_b128 v[170:173], v140 offset:3072
	ds_read_b128 v[174:177], v140 offset:4096
	ds_read_b128 v[178:181], v140 offset:5120
	ds_read_b128 v[182:185], v140 offset:6144
	ds_read_b128 v[186:189], v140 offset:7168
	global_load_lds_dwordx4 v[190:191], off
	v_lshl_add_u64 v[190:191], s[28:29], 0, v[134:135]
	s_add_i32 m0, s25, 0xe000
	s_nop 0
	global_load_lds_dwordx4 v[190:191], off
	s_waitcnt lgkmcnt(8)
	s_barrier
	s_waitcnt lgkmcnt(0)
	s_setprio 1
	s_waitcnt lgkmcnt(0)
	v_mfma_f32_16x16x32_bf16 v[124:127], v[142:145], v[158:161], v[124:127]
	v_mfma_f32_16x16x32_bf16 v[120:123], v[150:153], v[158:161], v[120:123]
	v_mfma_f32_16x16x32_bf16 v[108:111], v[142:145], v[166:169], v[108:111]
	v_mfma_f32_16x16x32_bf16 v[104:107], v[150:153], v[166:169], v[104:107]
	v_mfma_f32_16x16x32_bf16 v[92:95], v[142:145], v[174:177], v[92:95]
	v_mfma_f32_16x16x32_bf16 v[88:91], v[150:153], v[174:177], v[88:91]
	v_mfma_f32_16x16x32_bf16 v[76:79], v[142:145], v[182:185], v[76:79]
	v_mfma_f32_16x16x32_bf16 v[72:75], v[150:153], v[182:185], v[72:75]
	v_mfma_f32_16x16x32_bf16 v[124:127], v[146:149], v[162:165], v[124:127]
	v_mfma_f32_16x16x32_bf16 v[120:123], v[154:157], v[162:165], v[120:123]
	v_mfma_f32_16x16x32_bf16 v[108:111], v[146:149], v[170:173], v[108:111]
	v_mfma_f32_16x16x32_bf16 v[104:107], v[154:157], v[170:173], v[104:107]
	v_mfma_f32_16x16x32_bf16 v[92:95], v[146:149], v[178:181], v[92:95]
	v_mfma_f32_16x16x32_bf16 v[88:91], v[154:157], v[178:181], v[88:91]
	v_mfma_f32_16x16x32_bf16 v[76:79], v[146:149], v[186:189], v[76:79]
	v_mfma_f32_16x16x32_bf16 v[72:75], v[154:157], v[186:189], v[72:75]
	s_setprio 0
	s_barrier
	s_add_i32 s0, s45, s33
	v_lshl_add_u64 v[202:203], s[30:31], 0, v[130:131]
	s_mov_b32 m0, s0
	ds_read_b128 v[190:193], v141
	ds_read_b128 v[194:197], v141 offset:1024
	ds_read_b128 v[198:201], v141 offset:2048
	ds_read_b128 v[206:209], v141 offset:3072
	global_load_lds_dwordx4 v[202:203], off
	v_lshl_add_u64 v[210:211], s[30:31], 0, v[128:129]
	s_add_i32 m0, s0, 0x2000
	s_nop 0
	global_load_lds_dwordx4 v[210:211], off
	s_barrier
	s_waitcnt lgkmcnt(0)
	s_setprio 1
	s_waitcnt lgkmcnt(0)
	v_mfma_f32_16x16x32_bf16 v[116:119], v[190:193], v[158:161], v[116:119]
	v_mfma_f32_16x16x32_bf16 v[112:115], v[198:201], v[158:161], v[112:115]
	v_mfma_f32_16x16x32_bf16 v[100:103], v[190:193], v[166:169], v[100:103]
	v_mfma_f32_16x16x32_bf16 v[96:99], v[198:201], v[166:169], v[96:99]
	v_mfma_f32_16x16x32_bf16 v[84:87], v[190:193], v[174:177], v[84:87]
	v_mfma_f32_16x16x32_bf16 v[80:83], v[198:201], v[174:177], v[80:83]
	v_mfma_f32_16x16x32_bf16 v[68:71], v[190:193], v[182:185], v[68:71]
	v_mfma_f32_16x16x32_bf16 v[64:67], v[198:201], v[182:185], v[64:67]
	v_mfma_f32_16x16x32_bf16 v[116:119], v[194:197], v[162:165], v[116:119]
	v_mfma_f32_16x16x32_bf16 v[112:115], v[206:209], v[162:165], v[112:115]
	v_mfma_f32_16x16x32_bf16 v[100:103], v[194:197], v[170:173], v[100:103]
	v_mfma_f32_16x16x32_bf16 v[96:99], v[206:209], v[170:173], v[96:99]
	v_mfma_f32_16x16x32_bf16 v[84:87], v[194:197], v[178:181], v[84:87]
	v_mfma_f32_16x16x32_bf16 v[80:83], v[206:209], v[178:181], v[80:83]
	v_mfma_f32_16x16x32_bf16 v[68:71], v[194:197], v[186:189], v[68:71]
	v_mfma_f32_16x16x32_bf16 v[64:67], v[206:209], v[186:189], v[64:67]
	s_setprio 0
	s_mov_b32 m0, s25
	v_lshl_add_u64 v[212:213], s[34:35], 0, v[130:131]
	s_barrier
	ds_read_b128 v[158:161], v140 offset:16384
	ds_read_b128 v[162:165], v140 offset:17408
	ds_read_b128 v[166:169], v140 offset:18432
	ds_read_b128 v[170:173], v140 offset:19456
	ds_read_b128 v[174:177], v140 offset:20480
	ds_read_b128 v[178:181], v140 offset:21504
	ds_read_b128 v[182:185], v140 offset:22528
	ds_read_b128 v[186:189], v140 offset:23552
	global_load_lds_dwordx4 v[212:213], off
	v_lshl_add_u64 v[214:215], s[34:35], 0, v[128:129]
	s_mov_b32 m0, s27
	s_nop 0
	global_load_lds_dwordx4 v[214:215], off
	s_barrier
	s_waitcnt lgkmcnt(0)
	s_setprio 1
	s_waitcnt lgkmcnt(0)
	v_mfma_f32_16x16x32_bf16 v[60:63], v[142:145], v[158:161], v[60:63]
	v_mfma_f32_16x16x32_bf16 v[56:59], v[150:153], v[158:161], v[56:59]
	v_mfma_f32_16x16x32_bf16 v[44:47], v[142:145], v[166:169], v[44:47]
	v_mfma_f32_16x16x32_bf16 v[40:43], v[150:153], v[166:169], v[40:43]
	v_mfma_f32_16x16x32_bf16 v[28:31], v[142:145], v[174:177], v[28:31]
	v_mfma_f32_16x16x32_bf16 v[24:27], v[150:153], v[174:177], v[24:27]
	v_mfma_f32_16x16x32_bf16 v[12:15], v[142:145], v[182:185], v[12:15]
	v_mfma_f32_16x16x32_bf16 v[8:11], v[150:153], v[182:185], v[8:11]
	v_mfma_f32_16x16x32_bf16 v[60:63], v[146:149], v[162:165], v[60:63]
	v_mfma_f32_16x16x32_bf16 v[56:59], v[154:157], v[162:165], v[56:59]
	v_mfma_f32_16x16x32_bf16 v[44:47], v[146:149], v[170:173], v[44:47]
	v_mfma_f32_16x16x32_bf16 v[40:43], v[154:157], v[170:173], v[40:43]
	v_mfma_f32_16x16x32_bf16 v[28:31], v[146:149], v[178:181], v[28:31]
	v_mfma_f32_16x16x32_bf16 v[24:27], v[154:157], v[178:181], v[24:27]
	v_mfma_f32_16x16x32_bf16 v[12:15], v[146:149], v[186:189], v[12:15]
	v_mfma_f32_16x16x32_bf16 v[8:11], v[154:157], v[186:189], v[8:11]
	s_setprio 0
	s_barrier
	s_add_u32 s0, s30, 0x80000
	s_addc_u32 s1, s31, 0
	s_add_i32 s56, s46, s33
	v_lshl_add_u64 v[142:143], s[0:1], 0, v[130:131]
	s_mov_b32 m0, s56
	s_nop 0
	global_load_lds_dwordx4 v[142:143], off
	v_lshl_add_u64 v[142:143], s[0:1], 0, v[128:129]
	s_add_i32 m0, s56, 0x2000
	s_nop 0
	global_load_lds_dwordx4 v[142:143], off
	s_waitcnt vmcnt(6)
	s_barrier
	s_setprio 1
	v_mfma_f32_16x16x32_bf16 v[52:55], v[190:193], v[158:161], v[52:55]
	v_mfma_f32_16x16x32_bf16 v[48:51], v[198:201], v[158:161], v[48:51]
	v_mfma_f32_16x16x32_bf16 v[36:39], v[190:193], v[166:169], v[36:39]
	v_mfma_f32_16x16x32_bf16 v[32:35], v[198:201], v[166:169], v[32:35]
	v_mfma_f32_16x16x32_bf16 v[20:23], v[190:193], v[174:177], v[20:23]
	v_mfma_f32_16x16x32_bf16 v[16:19], v[198:201], v[174:177], v[16:19]
	v_mfma_f32_16x16x32_bf16 v[4:7], v[190:193], v[182:185], v[4:7]
	v_mfma_f32_16x16x32_bf16 v[0:3], v[198:201], v[182:185], v[0:3]
	v_mfma_f32_16x16x32_bf16 v[52:55], v[194:197], v[162:165], v[52:55]
	v_mfma_f32_16x16x32_bf16 v[48:51], v[206:209], v[162:165], v[48:51]
	v_mfma_f32_16x16x32_bf16 v[36:39], v[194:197], v[170:173], v[36:39]
	v_mfma_f32_16x16x32_bf16 v[32:35], v[206:209], v[170:173], v[32:35]
	v_mfma_f32_16x16x32_bf16 v[20:23], v[194:197], v[178:181], v[20:23]
	v_mfma_f32_16x16x32_bf16 v[16:19], v[206:209], v[178:181], v[16:19]
	v_mfma_f32_16x16x32_bf16 v[4:7], v[194:197], v[186:189], v[4:7]
	v_mfma_f32_16x16x32_bf16 v[0:3], v[206:209], v[186:189], v[0:3]
	s_setprio 0
	s_add_i32 s56, 16, 0x18000
	v_add_u32_e32 v154, s56, v137
	s_barrier
	ds_read_b128 v[142:145], v154
	ds_read_b128 v[146:149], v154 offset:1024
	ds_read_b128 v[150:153], v154 offset:2048
	ds_read_b128 v[154:157], v154 offset:3072
	s_add_u32 s0, s34, 0x80000
	s_addc_u32 s1, s35, 0
	s_mov_b32 m0, s40
	v_lshl_add_u64 v[190:191], s[0:1], 0, v[130:131]
	ds_read_b128 v[158:161], v140 offset:32768
	ds_read_b128 v[162:165], v140 offset:33792
	ds_read_b128 v[166:169], v140 offset:34816
	ds_read_b128 v[170:173], v140 offset:35840
	ds_read_b128 v[174:177], v140 offset:36864
	ds_read_b128 v[178:181], v140 offset:37888
	ds_read_b128 v[182:185], v140 offset:38912
	ds_read_b128 v[186:189], v140 offset:39936
	global_load_lds_dwordx4 v[190:191], off
	v_lshl_add_u64 v[190:191], s[0:1], 0, v[128:129]
	s_mov_b32 m0, s41
	s_nop 0
	global_load_lds_dwordx4 v[190:191], off
	s_waitcnt lgkmcnt(8)
	s_barrier
	s_waitcnt lgkmcnt(0)
	s_setprio 1
	s_waitcnt lgkmcnt(0)
	v_mfma_f32_16x16x32_bf16 v[124:127], v[142:145], v[158:161], v[124:127]
	v_mfma_f32_16x16x32_bf16 v[120:123], v[150:153], v[158:161], v[120:123]
	v_mfma_f32_16x16x32_bf16 v[108:111], v[142:145], v[166:169], v[108:111]
	v_mfma_f32_16x16x32_bf16 v[104:107], v[150:153], v[166:169], v[104:107]
	v_mfma_f32_16x16x32_bf16 v[92:95], v[142:145], v[174:177], v[92:95]
	v_mfma_f32_16x16x32_bf16 v[88:91], v[150:153], v[174:177], v[88:91]
	v_mfma_f32_16x16x32_bf16 v[76:79], v[142:145], v[182:185], v[76:79]
	v_mfma_f32_16x16x32_bf16 v[72:75], v[150:153], v[182:185], v[72:75]
	v_mfma_f32_16x16x32_bf16 v[124:127], v[146:149], v[162:165], v[124:127]
	v_mfma_f32_16x16x32_bf16 v[120:123], v[154:157], v[162:165], v[120:123]
	v_mfma_f32_16x16x32_bf16 v[108:111], v[146:149], v[170:173], v[108:111]
	v_mfma_f32_16x16x32_bf16 v[104:107], v[154:157], v[170:173], v[104:107]
	v_mfma_f32_16x16x32_bf16 v[92:95], v[146:149], v[178:181], v[92:95]
	v_mfma_f32_16x16x32_bf16 v[88:91], v[154:157], v[178:181], v[88:91]
	v_mfma_f32_16x16x32_bf16 v[76:79], v[146:149], v[186:189], v[76:79]
	v_mfma_f32_16x16x32_bf16 v[72:75], v[154:157], v[186:189], v[72:75]
	s_setprio 0
	s_barrier
	s_add_i32 s34, 16, 0x1c000
	s_add_i32 s0, s56, s33
	v_add_u32_e32 v205, s34, v137
	v_lshl_add_u64 v[202:203], v[202:203], 0, s[4:5]
	s_mov_b32 m0, s0
	ds_read_b128 v[190:193], v205
	ds_read_b128 v[194:197], v205 offset:1024
	ds_read_b128 v[198:201], v205 offset:2048
	ds_read_b128 v[206:209], v205 offset:3072
	global_load_lds_dwordx4 v[202:203], off
	v_lshl_add_u64 v[202:203], v[210:211], 0, s[4:5]
	s_add_i32 m0, s0, 0x2000
	s_nop 0
	global_load_lds_dwordx4 v[202:203], off
	s_barrier
	s_waitcnt lgkmcnt(0)
	s_setprio 1
	s_waitcnt lgkmcnt(0)
	v_mfma_f32_16x16x32_bf16 v[116:119], v[190:193], v[158:161], v[116:119]
	v_mfma_f32_16x16x32_bf16 v[112:115], v[198:201], v[158:161], v[112:115]
	v_mfma_f32_16x16x32_bf16 v[100:103], v[190:193], v[166:169], v[100:103]
	v_mfma_f32_16x16x32_bf16 v[96:99], v[198:201], v[166:169], v[96:99]
	v_mfma_f32_16x16x32_bf16 v[84:87], v[190:193], v[174:177], v[84:87]
	v_mfma_f32_16x16x32_bf16 v[80:83], v[198:201], v[174:177], v[80:83]
	v_mfma_f32_16x16x32_bf16 v[68:71], v[190:193], v[182:185], v[68:71]
	v_mfma_f32_16x16x32_bf16 v[64:67], v[198:201], v[182:185], v[64:67]
	v_mfma_f32_16x16x32_bf16 v[116:119], v[194:197], v[162:165], v[116:119]
	v_mfma_f32_16x16x32_bf16 v[112:115], v[206:209], v[162:165], v[112:115]
	v_mfma_f32_16x16x32_bf16 v[100:103], v[194:197], v[170:173], v[100:103]
	v_mfma_f32_16x16x32_bf16 v[96:99], v[206:209], v[170:173], v[96:99]
	v_mfma_f32_16x16x32_bf16 v[84:87], v[194:197], v[178:181], v[84:87]
	v_mfma_f32_16x16x32_bf16 v[80:83], v[206:209], v[178:181], v[80:83]
	v_mfma_f32_16x16x32_bf16 v[68:71], v[194:197], v[186:189], v[68:71]
	v_mfma_f32_16x16x32_bf16 v[64:67], v[206:209], v[186:189], v[64:67]
	s_setprio 0
	s_mov_b32 m0, s42
	v_lshl_add_u64 v[202:203], v[212:213], 0, s[4:5]
	s_barrier
	ds_read_b128 v[158:161], v140 offset:49152
	ds_read_b128 v[162:165], v140 offset:50176
	ds_read_b128 v[166:169], v140 offset:51200
	ds_read_b128 v[170:173], v140 offset:52224
	ds_read_b128 v[174:177], v140 offset:53248
	ds_read_b128 v[178:181], v140 offset:54272
	ds_read_b128 v[182:185], v140 offset:55296
	ds_read_b128 v[186:189], v140 offset:56320
	global_load_lds_dwordx4 v[202:203], off
	v_lshl_add_u64 v[202:203], v[214:215], 0, s[4:5]
	s_mov_b32 m0, s43
	s_nop 0
	global_load_lds_dwordx4 v[202:203], off
	s_barrier
	s_waitcnt lgkmcnt(0)
	s_setprio 1
	s_waitcnt lgkmcnt(0)
	v_mfma_f32_16x16x32_bf16 v[60:63], v[142:145], v[158:161], v[60:63]
	v_mfma_f32_16x16x32_bf16 v[56:59], v[150:153], v[158:161], v[56:59]
	v_mfma_f32_16x16x32_bf16 v[44:47], v[142:145], v[166:169], v[44:47]
	v_mfma_f32_16x16x32_bf16 v[40:43], v[150:153], v[166:169], v[40:43]
	v_mfma_f32_16x16x32_bf16 v[28:31], v[142:145], v[174:177], v[28:31]
	v_mfma_f32_16x16x32_bf16 v[24:27], v[150:153], v[174:177], v[24:27]
	v_mfma_f32_16x16x32_bf16 v[12:15], v[142:145], v[182:185], v[12:15]
	v_mfma_f32_16x16x32_bf16 v[8:11], v[150:153], v[182:185], v[8:11]
	v_mfma_f32_16x16x32_bf16 v[60:63], v[146:149], v[162:165], v[60:63]
	v_mfma_f32_16x16x32_bf16 v[56:59], v[154:157], v[162:165], v[56:59]
	v_mfma_f32_16x16x32_bf16 v[44:47], v[146:149], v[170:173], v[44:47]
	v_mfma_f32_16x16x32_bf16 v[40:43], v[154:157], v[170:173], v[40:43]
	v_mfma_f32_16x16x32_bf16 v[28:31], v[146:149], v[178:181], v[28:31]
	v_mfma_f32_16x16x32_bf16 v[24:27], v[154:157], v[178:181], v[24:27]
	v_mfma_f32_16x16x32_bf16 v[12:15], v[146:149], v[186:189], v[12:15]
	v_mfma_f32_16x16x32_bf16 v[8:11], v[154:157], v[186:189], v[8:11]
	s_setprio 0
	s_barrier
	s_add_u32 s0, s30, 0x80080
	s_addc_u32 s1, s31, 0
	s_add_i32 s30, s34, s33
	v_lshl_add_u64 v[142:143], s[0:1], 0, v[130:131]
	s_mov_b32 m0, s30
	s_nop 0
	global_load_lds_dwordx4 v[142:143], off
	v_lshl_add_u64 v[142:143], s[0:1], 0, v[128:129]
	s_add_i32 m0, s30, 0x2000
	s_nop 0
	global_load_lds_dwordx4 v[142:143], off
	s_waitcnt vmcnt(6)
	s_barrier
	s_setprio 1
	v_mfma_f32_16x16x32_bf16 v[52:55], v[190:193], v[158:161], v[52:55]
	v_mfma_f32_16x16x32_bf16 v[48:51], v[198:201], v[158:161], v[48:51]
	v_mfma_f32_16x16x32_bf16 v[36:39], v[190:193], v[166:169], v[36:39]
	v_mfma_f32_16x16x32_bf16 v[32:35], v[198:201], v[166:169], v[32:35]
	v_mfma_f32_16x16x32_bf16 v[20:23], v[190:193], v[174:177], v[20:23]
	v_mfma_f32_16x16x32_bf16 v[16:19], v[198:201], v[174:177], v[16:19]
	v_mfma_f32_16x16x32_bf16 v[4:7], v[190:193], v[182:185], v[4:7]
	v_mfma_f32_16x16x32_bf16 v[0:3], v[198:201], v[182:185], v[0:3]
	v_mfma_f32_16x16x32_bf16 v[52:55], v[194:197], v[162:165], v[52:55]
	v_mfma_f32_16x16x32_bf16 v[48:51], v[206:209], v[162:165], v[48:51]
	v_mfma_f32_16x16x32_bf16 v[36:39], v[194:197], v[170:173], v[36:39]
	v_mfma_f32_16x16x32_bf16 v[32:35], v[206:209], v[170:173], v[32:35]
	v_mfma_f32_16x16x32_bf16 v[20:23], v[194:197], v[178:181], v[20:23]
	v_mfma_f32_16x16x32_bf16 v[16:19], v[206:209], v[178:181], v[16:19]
	v_mfma_f32_16x16x32_bf16 v[4:7], v[194:197], v[186:189], v[4:7]
	v_mfma_f32_16x16x32_bf16 v[0:3], v[206:209], v[186:189], v[0:3]
	s_setprio 0
	s_add_i32 s55, s55, 2
	s_add_u32 s28, s28, 0x100
	s_addc_u32 s29, s29, 0
	s_add_u32 s53, s53, 0x100
	s_addc_u32 s54, s54, 0
	s_cmp_gt_u32 s55, 29
	s_barrier
	s_cbranch_scc0 .LBB0_1492
	v_lshl_add_u32 v142, s26, 8, v136
	v_max_f32_e32 v126, v126, v126
	v_max_f32_e32 v127, v127, v127
	v_lshl_or_b32 v144, s24, 8, v138
	v_ashrrev_i32_e32 v143, 31, v142
	v_max_f32_e32 v124, v124, v124
	v_max_f32_e32 v120, v120, v120
	v_max_f32_e32 v125, v125, v125
	v_max_f32_e32 v121, v121, v121
	v_max_f32_e32 v126, 0, v126
	v_max_f32_e32 v122, v122, v122
	v_max_f32_e32 v127, 0, v127
	v_max_f32_e32 v123, v123, v123
	v_lshlrev_b64 v[146:147], 14, v[142:143]
	v_max_f32_e32 v124, 0, v124
	v_max_f32_e32 v120, 0, v120
	v_max_f32_e32 v125, 0, v125
	v_max_f32_e32 v121, 0, v121
	v_max_f32_e32 v122, 0, v122
	v_pk_mul_f32 v[126:127], v[126:127], v[126:127]
	v_max_f32_e32 v123, 0, v123
	v_ashrrev_i32_e32 v145, 31, v144
	v_lshl_add_u64 v[146:147], s[76:77], 0, v[146:147]
	v_pk_mul_f32 v[124:125], v[124:125], v[124:125]
	v_pk_mul_f32 v[120:121], v[120:121], v[120:121]
	v_pk_mul_f32 v[148:149], v[122:123], v[122:123]
	v_cvt_pk_bf16_f32 v123, v126, v127
	v_lshlrev_b64 v[126:127], 1, v[144:145]
	v_max_f32_e32 v112, v112, v112
	v_max_f32_e32 v113, v113, v113
	v_cvt_pk_bf16_f32 v122, v124, v125
	v_cvt_pk_bf16_f32 v124, v120, v121
	v_cvt_pk_bf16_f32 v125, v148, v149
	v_lshl_add_u64 v[120:121], v[146:147], 0, v[126:127]
	v_max_f32_e32 v112, 0, v112
	v_max_f32_e32 v113, 0, v113
	global_store_dwordx4 v[120:121], v[122:125], off nt
	v_max_f32_e32 v116, v116, v116
	v_max_f32_e32 v117, v117, v117
	v_pk_mul_f32 v[122:123], v[112:113], v[112:113]
	v_max_f32_e32 v113, v114, v114
	v_max_f32_e32 v112, v118, v118
	v_max_f32_e32 v114, 0, v113
	v_max_f32_e32 v113, v119, v119
	v_max_f32_e32 v112, 0, v112
	v_max_f32_e32 v113, 0, v113
	v_pk_mul_f32 v[118:119], v[112:113], v[112:113]
	v_max_f32_e32 v112, v115, v115
	v_max_f32_e32 v116, 0, v116
	v_max_f32_e32 v117, 0, v117
	v_max_f32_e32 v115, 0, v112
	v_pk_mul_f32 v[116:117], v[116:117], v[116:117]
	v_pk_mul_f32 v[124:125], v[114:115], v[114:115]
	v_max_f32_e32 v104, v104, v104
	v_max_f32_e32 v105, v105, v105
	v_cvt_pk_bf16_f32 v112, v116, v117
	v_cvt_pk_bf16_f32 v113, v118, v119
	v_cvt_pk_bf16_f32 v114, v122, v123
	v_cvt_pk_bf16_f32 v115, v124, v125
	v_max_f32_e32 v104, 0, v104
	v_max_f32_e32 v105, 0, v105
	global_store_dwordx4 v[120:121], v[112:115], off offset:256 nt
	v_max_f32_e32 v108, v108, v108
	v_max_f32_e32 v109, v109, v109
	v_pk_mul_f32 v[114:115], v[104:105], v[104:105]
	v_max_f32_e32 v105, v106, v106
	v_max_f32_e32 v104, v110, v110
	v_max_f32_e32 v106, 0, v105
	v_max_f32_e32 v105, v111, v111
	v_or_b32_e32 v112, 16, v142
	v_max_f32_e32 v104, 0, v104
	v_max_f32_e32 v105, 0, v105
	v_ashrrev_i32_e32 v113, 31, v112
	v_pk_mul_f32 v[110:111], v[104:105], v[104:105]
	v_max_f32_e32 v104, v107, v107
	v_lshlrev_b64 v[112:113], 14, v[112:113]
	v_max_f32_e32 v108, 0, v108
	v_max_f32_e32 v109, 0, v109
	v_max_f32_e32 v107, 0, v104
	v_lshl_add_u64 v[112:113], s[76:77], 0, v[112:113]
	v_pk_mul_f32 v[108:109], v[108:109], v[108:109]
	v_pk_mul_f32 v[116:117], v[106:107], v[106:107]
	v_max_f32_e32 v96, v96, v96
	v_max_f32_e32 v97, v97, v97
	v_cvt_pk_bf16_f32 v104, v108, v109
	v_cvt_pk_bf16_f32 v105, v110, v111
	v_cvt_pk_bf16_f32 v106, v114, v115
	v_cvt_pk_bf16_f32 v107, v116, v117
	v_lshl_add_u64 v[108:109], v[112:113], 0, v[126:127]
	v_max_f32_e32 v96, 0, v96
	v_max_f32_e32 v97, 0, v97
	global_store_dwordx4 v[108:109], v[104:107], off nt
	v_max_f32_e32 v100, v100, v100
	v_max_f32_e32 v101, v101, v101
	v_pk_mul_f32 v[104:105], v[96:97], v[96:97]
	v_max_f32_e32 v97, v98, v98
	v_max_f32_e32 v96, v102, v102
	v_max_f32_e32 v98, 0, v97
	v_max_f32_e32 v97, v103, v103
	v_max_f32_e32 v96, 0, v96
	v_max_f32_e32 v97, 0, v97
	v_pk_mul_f32 v[102:103], v[96:97], v[96:97]
	v_max_f32_e32 v96, v99, v99
	v_max_f32_e32 v100, 0, v100
	v_max_f32_e32 v101, 0, v101
	v_max_f32_e32 v99, 0, v96
	v_pk_mul_f32 v[100:101], v[100:101], v[100:101]
	v_pk_mul_f32 v[106:107], v[98:99], v[98:99]
	v_max_f32_e32 v88, v88, v88
	v_max_f32_e32 v89, v89, v89
	v_cvt_pk_bf16_f32 v96, v100, v101
	v_cvt_pk_bf16_f32 v97, v102, v103
	v_cvt_pk_bf16_f32 v98, v104, v105
	v_cvt_pk_bf16_f32 v99, v106, v107
	v_max_f32_e32 v88, 0, v88
	v_max_f32_e32 v89, 0, v89
	global_store_dwordx4 v[108:109], v[96:99], off offset:256 nt
	v_max_f32_e32 v92, v92, v92
	v_max_f32_e32 v93, v93, v93
	v_pk_mul_f32 v[98:99], v[88:89], v[88:89]
	v_max_f32_e32 v89, v90, v90
	v_max_f32_e32 v88, v94, v94
	v_max_f32_e32 v90, 0, v89
	v_max_f32_e32 v89, v95, v95
	v_or_b32_e32 v96, 32, v142
	v_max_f32_e32 v88, 0, v88
	v_max_f32_e32 v89, 0, v89
	v_ashrrev_i32_e32 v97, 31, v96
	v_pk_mul_f32 v[94:95], v[88:89], v[88:89]
	v_max_f32_e32 v88, v91, v91
	v_lshlrev_b64 v[96:97], 14, v[96:97]
	v_max_f32_e32 v92, 0, v92
	v_max_f32_e32 v93, 0, v93
	v_max_f32_e32 v91, 0, v88
	v_lshl_add_u64 v[96:97], s[76:77], 0, v[96:97]
	v_pk_mul_f32 v[92:93], v[92:93], v[92:93]
	v_pk_mul_f32 v[100:101], v[90:91], v[90:91]
	v_max_f32_e32 v80, v80, v80
	v_max_f32_e32 v81, v81, v81
	v_cvt_pk_bf16_f32 v88, v92, v93
	v_cvt_pk_bf16_f32 v89, v94, v95
	v_cvt_pk_bf16_f32 v90, v98, v99
	v_cvt_pk_bf16_f32 v91, v100, v101
	v_lshl_add_u64 v[92:93], v[96:97], 0, v[126:127]
	v_max_f32_e32 v80, 0, v80
	v_max_f32_e32 v81, 0, v81
	global_store_dwordx4 v[92:93], v[88:91], off nt
	v_max_f32_e32 v84, v84, v84
	v_max_f32_e32 v85, v85, v85
	v_pk_mul_f32 v[88:89], v[80:81], v[80:81]
	v_max_f32_e32 v81, v82, v82
	v_max_f32_e32 v80, v86, v86
	v_max_f32_e32 v82, 0, v81
	v_max_f32_e32 v81, v87, v87
	v_max_f32_e32 v80, 0, v80
	v_max_f32_e32 v81, 0, v81
	v_pk_mul_f32 v[86:87], v[80:81], v[80:81]
	v_max_f32_e32 v80, v83, v83
	v_max_f32_e32 v84, 0, v84
	v_max_f32_e32 v85, 0, v85
	v_max_f32_e32 v83, 0, v80
	v_pk_mul_f32 v[84:85], v[84:85], v[84:85]
	v_pk_mul_f32 v[90:91], v[82:83], v[82:83]
	v_max_f32_e32 v72, v72, v72
	v_max_f32_e32 v73, v73, v73
	v_cvt_pk_bf16_f32 v80, v84, v85
	v_cvt_pk_bf16_f32 v81, v86, v87
	v_cvt_pk_bf16_f32 v82, v88, v89
	v_cvt_pk_bf16_f32 v83, v90, v91
	v_max_f32_e32 v72, 0, v72
	v_max_f32_e32 v73, 0, v73
	global_store_dwordx4 v[92:93], v[80:83], off offset:256 nt
	v_max_f32_e32 v76, v76, v76
	v_max_f32_e32 v77, v77, v77
	v_pk_mul_f32 v[82:83], v[72:73], v[72:73]
	v_max_f32_e32 v73, v74, v74
	v_max_f32_e32 v72, v78, v78
	v_max_f32_e32 v74, 0, v73
	v_max_f32_e32 v73, v79, v79
	v_or_b32_e32 v80, 48, v142
	v_max_f32_e32 v72, 0, v72
	v_max_f32_e32 v73, 0, v73
	v_ashrrev_i32_e32 v81, 31, v80
	v_pk_mul_f32 v[78:79], v[72:73], v[72:73]
	v_max_f32_e32 v72, v75, v75
	v_lshlrev_b64 v[80:81], 14, v[80:81]
	v_max_f32_e32 v76, 0, v76
	v_max_f32_e32 v77, 0, v77
	v_max_f32_e32 v75, 0, v72
	v_lshl_add_u64 v[80:81], s[76:77], 0, v[80:81]
	v_pk_mul_f32 v[76:77], v[76:77], v[76:77]
	v_pk_mul_f32 v[84:85], v[74:75], v[74:75]
	v_max_f32_e32 v64, v64, v64
	v_max_f32_e32 v65, v65, v65
	v_cvt_pk_bf16_f32 v72, v76, v77
	v_cvt_pk_bf16_f32 v73, v78, v79
	v_cvt_pk_bf16_f32 v74, v82, v83
	v_cvt_pk_bf16_f32 v75, v84, v85
	v_lshl_add_u64 v[76:77], v[80:81], 0, v[126:127]
	v_max_f32_e32 v64, 0, v64
	v_max_f32_e32 v65, 0, v65
	global_store_dwordx4 v[76:77], v[72:75], off nt
	v_max_f32_e32 v68, v68, v68
	v_max_f32_e32 v69, v69, v69
	v_pk_mul_f32 v[72:73], v[64:65], v[64:65]
	v_max_f32_e32 v65, v66, v66
	v_max_f32_e32 v64, v70, v70
	v_max_f32_e32 v66, 0, v65
	v_max_f32_e32 v65, v71, v71
	v_max_f32_e32 v64, 0, v64
	v_max_f32_e32 v65, 0, v65
	v_pk_mul_f32 v[70:71], v[64:65], v[64:65]
	v_max_f32_e32 v64, v67, v67
	v_max_f32_e32 v68, 0, v68
	v_max_f32_e32 v69, 0, v69
	v_max_f32_e32 v67, 0, v64
	v_pk_mul_f32 v[68:69], v[68:69], v[68:69]
	v_pk_mul_f32 v[74:75], v[66:67], v[66:67]
	v_max_f32_e32 v56, v56, v56
	v_max_f32_e32 v57, v57, v57
	v_cvt_pk_bf16_f32 v64, v68, v69
	v_cvt_pk_bf16_f32 v65, v70, v71
	v_cvt_pk_bf16_f32 v66, v72, v73
	v_cvt_pk_bf16_f32 v67, v74, v75
	v_max_f32_e32 v56, 0, v56
	v_max_f32_e32 v57, 0, v57
	global_store_dwordx4 v[76:77], v[64:67], off offset:256 nt
	v_max_f32_e32 v60, v60, v60
	v_max_f32_e32 v61, v61, v61
	v_pk_mul_f32 v[64:65], v[56:57], v[56:57]
	v_max_f32_e32 v57, v58, v58
	v_max_f32_e32 v56, v62, v62
	v_max_f32_e32 v58, 0, v57
	v_max_f32_e32 v57, v63, v63
	v_max_f32_e32 v56, 0, v56
	v_max_f32_e32 v57, 0, v57
	v_pk_mul_f32 v[62:63], v[56:57], v[56:57]
	v_max_f32_e32 v56, v59, v59
	v_max_f32_e32 v60, 0, v60
	v_max_f32_e32 v61, 0, v61
	v_max_f32_e32 v59, 0, v56
	v_pk_mul_f32 v[60:61], v[60:61], v[60:61]
	v_pk_mul_f32 v[66:67], v[58:59], v[58:59]
	v_cvt_pk_bf16_f32 v57, v62, v63
	v_add_co_u32_e32 v62, vcc, s47, v120
	v_max_f32_e32 v48, v48, v48
	v_max_f32_e32 v49, v49, v49
	v_cvt_pk_bf16_f32 v56, v60, v61
	v_cvt_pk_bf16_f32 v58, v64, v65
	v_cvt_pk_bf16_f32 v59, v66, v67
	v_addc_co_u32_e32 v63, vcc, 0, v121, vcc
	v_max_f32_e32 v48, 0, v48
	v_max_f32_e32 v49, 0, v49
	global_store_dwordx4 v[62:63], v[56:59], off nt
	v_max_f32_e32 v52, v52, v52
	v_max_f32_e32 v53, v53, v53
	v_pk_mul_f32 v[56:57], v[48:49], v[48:49]
	v_max_f32_e32 v49, v50, v50
	v_max_f32_e32 v48, v54, v54
	v_max_f32_e32 v50, 0, v49
	v_max_f32_e32 v49, v55, v55
	v_max_f32_e32 v48, 0, v48
	v_max_f32_e32 v49, 0, v49
	v_pk_mul_f32 v[54:55], v[48:49], v[48:49]
	v_max_f32_e32 v48, v51, v51
	v_max_f32_e32 v52, 0, v52
	v_max_f32_e32 v53, 0, v53
	v_max_f32_e32 v51, 0, v48
	v_pk_mul_f32 v[52:53], v[52:53], v[52:53]
	v_pk_mul_f32 v[58:59], v[50:51], v[50:51]
	v_max_f32_e32 v40, v40, v40
	v_max_f32_e32 v41, v41, v41
	v_lshl_add_u64 v[60:61], v[120:121], 0, s[6:7]
	v_cvt_pk_bf16_f32 v48, v52, v53
	v_cvt_pk_bf16_f32 v49, v54, v55
	v_cvt_pk_bf16_f32 v50, v56, v57
	v_cvt_pk_bf16_f32 v51, v58, v59
	v_max_f32_e32 v40, 0, v40
	v_max_f32_e32 v41, 0, v41
	global_store_dwordx4 v[60:61], v[48:51], off offset:256 nt
	v_max_f32_e32 v44, v44, v44
	v_max_f32_e32 v45, v45, v45
	v_pk_mul_f32 v[48:49], v[40:41], v[40:41]
	v_max_f32_e32 v41, v42, v42
	v_max_f32_e32 v40, v46, v46
	v_max_f32_e32 v42, 0, v41
	v_max_f32_e32 v41, v47, v47
	v_max_f32_e32 v40, 0, v40
	v_max_f32_e32 v41, 0, v41
	v_pk_mul_f32 v[46:47], v[40:41], v[40:41]
	v_max_f32_e32 v40, v43, v43
	v_max_f32_e32 v44, 0, v44
	v_max_f32_e32 v45, 0, v45
	v_max_f32_e32 v43, 0, v40
	v_pk_mul_f32 v[44:45], v[44:45], v[44:45]
	v_pk_mul_f32 v[50:51], v[42:43], v[42:43]
	v_cvt_pk_bf16_f32 v41, v46, v47
	v_add_co_u32_e32 v46, vcc, s48, v120
	v_max_f32_e32 v32, v32, v32
	v_max_f32_e32 v33, v33, v33
	v_cvt_pk_bf16_f32 v40, v44, v45
	v_cvt_pk_bf16_f32 v42, v48, v49
	v_cvt_pk_bf16_f32 v43, v50, v51
	v_addc_co_u32_e32 v47, vcc, 0, v121, vcc
	v_max_f32_e32 v32, 0, v32
	v_max_f32_e32 v33, 0, v33
	global_store_dwordx4 v[46:47], v[40:43], off nt
	v_max_f32_e32 v36, v36, v36
	v_max_f32_e32 v37, v37, v37
	v_pk_mul_f32 v[40:41], v[32:33], v[32:33]
	v_max_f32_e32 v33, v34, v34
	v_max_f32_e32 v32, v38, v38
	v_max_f32_e32 v34, 0, v33
	v_max_f32_e32 v33, v39, v39
	v_max_f32_e32 v32, 0, v32
	v_max_f32_e32 v33, 0, v33
	v_pk_mul_f32 v[38:39], v[32:33], v[32:33]
	v_max_f32_e32 v32, v35, v35
	v_max_f32_e32 v36, 0, v36
	v_max_f32_e32 v37, 0, v37
	v_max_f32_e32 v35, 0, v32
	v_pk_mul_f32 v[36:37], v[36:37], v[36:37]
	v_pk_mul_f32 v[42:43], v[34:35], v[34:35]
	v_max_f32_e32 v24, v24, v24
	v_max_f32_e32 v25, v25, v25
	v_lshl_add_u64 v[44:45], v[120:121], 0, s[8:9]
	v_cvt_pk_bf16_f32 v32, v36, v37
	v_cvt_pk_bf16_f32 v33, v38, v39
	v_cvt_pk_bf16_f32 v34, v40, v41
	v_cvt_pk_bf16_f32 v35, v42, v43
	v_max_f32_e32 v24, 0, v24
	v_max_f32_e32 v25, 0, v25
	global_store_dwordx4 v[44:45], v[32:35], off offset:256 nt
	v_max_f32_e32 v28, v28, v28
	v_max_f32_e32 v29, v29, v29
	v_pk_mul_f32 v[32:33], v[24:25], v[24:25]
	v_max_f32_e32 v25, v26, v26
	v_max_f32_e32 v24, v30, v30
	v_max_f32_e32 v26, 0, v25
	v_max_f32_e32 v25, v31, v31
	v_max_f32_e32 v24, 0, v24
	v_max_f32_e32 v25, 0, v25
	v_pk_mul_f32 v[30:31], v[24:25], v[24:25]
	v_max_f32_e32 v24, v27, v27
	v_max_f32_e32 v28, 0, v28
	v_max_f32_e32 v29, 0, v29
	v_max_f32_e32 v27, 0, v24
	v_pk_mul_f32 v[28:29], v[28:29], v[28:29]
	v_pk_mul_f32 v[34:35], v[26:27], v[26:27]
	v_cvt_pk_bf16_f32 v25, v30, v31
	v_add_co_u32_e32 v30, vcc, s49, v120
	v_max_f32_e32 v16, v16, v16
	v_max_f32_e32 v17, v17, v17
	v_cvt_pk_bf16_f32 v24, v28, v29
	v_cvt_pk_bf16_f32 v26, v32, v33
	v_cvt_pk_bf16_f32 v27, v34, v35
	v_addc_co_u32_e32 v31, vcc, 0, v121, vcc
	v_max_f32_e32 v16, 0, v16
	v_max_f32_e32 v17, 0, v17
	global_store_dwordx4 v[30:31], v[24:27], off nt
	v_max_f32_e32 v20, v20, v20
	v_max_f32_e32 v21, v21, v21
	v_pk_mul_f32 v[24:25], v[16:17], v[16:17]
	v_max_f32_e32 v17, v18, v18
	v_max_f32_e32 v16, v22, v22
	v_max_f32_e32 v18, 0, v17
	v_max_f32_e32 v17, v23, v23
	v_max_f32_e32 v16, 0, v16
	v_max_f32_e32 v17, 0, v17
	v_pk_mul_f32 v[22:23], v[16:17], v[16:17]
	v_max_f32_e32 v16, v19, v19
	v_max_f32_e32 v20, 0, v20
	v_max_f32_e32 v21, 0, v21
	v_max_f32_e32 v19, 0, v16
	v_pk_mul_f32 v[20:21], v[20:21], v[20:21]
	v_pk_mul_f32 v[26:27], v[18:19], v[18:19]
	v_max_f32_e32 v8, v8, v8
	v_max_f32_e32 v9, v9, v9
	v_lshl_add_u64 v[28:29], v[120:121], 0, s[10:11]
	v_cvt_pk_bf16_f32 v16, v20, v21
	v_cvt_pk_bf16_f32 v17, v22, v23
	v_cvt_pk_bf16_f32 v18, v24, v25
	v_cvt_pk_bf16_f32 v19, v26, v27
	v_max_f32_e32 v8, 0, v8
	v_max_f32_e32 v9, 0, v9
	global_store_dwordx4 v[28:29], v[16:19], off offset:256 nt
	v_max_f32_e32 v12, v12, v12
	v_max_f32_e32 v13, v13, v13
	v_pk_mul_f32 v[16:17], v[8:9], v[8:9]
	v_max_f32_e32 v9, v10, v10
	v_max_f32_e32 v8, v14, v14
	v_max_f32_e32 v10, 0, v9
	v_max_f32_e32 v9, v15, v15
	v_max_f32_e32 v8, 0, v8
	v_max_f32_e32 v9, 0, v9
	v_pk_mul_f32 v[14:15], v[8:9], v[8:9]
	v_max_f32_e32 v8, v11, v11
	v_max_f32_e32 v12, 0, v12
	v_max_f32_e32 v13, 0, v13
	v_max_f32_e32 v11, 0, v8
	v_pk_mul_f32 v[12:13], v[12:13], v[12:13]
	v_pk_mul_f32 v[18:19], v[10:11], v[10:11]
	v_cvt_pk_bf16_f32 v9, v14, v15
	v_add_co_u32_e32 v14, vcc, s50, v120
	v_max_f32_e32 v0, v0, v0
	v_max_f32_e32 v1, v1, v1
	v_cvt_pk_bf16_f32 v8, v12, v13
	v_cvt_pk_bf16_f32 v10, v16, v17
	v_cvt_pk_bf16_f32 v11, v18, v19
	v_addc_co_u32_e32 v15, vcc, 0, v121, vcc
	v_max_f32_e32 v0, 0, v0
	v_max_f32_e32 v1, 0, v1
	global_store_dwordx4 v[14:15], v[8:11], off nt
	v_max_f32_e32 v4, v4, v4
	v_max_f32_e32 v5, v5, v5
	v_pk_mul_f32 v[8:9], v[0:1], v[0:1]
	v_max_f32_e32 v1, v2, v2
	v_max_f32_e32 v0, v6, v6
	v_max_f32_e32 v2, 0, v1
	v_max_f32_e32 v1, v7, v7
	v_max_f32_e32 v0, 0, v0
	v_max_f32_e32 v1, 0, v1
	v_pk_mul_f32 v[6:7], v[0:1], v[0:1]
	v_max_f32_e32 v0, v3, v3
	v_max_f32_e32 v4, 0, v4
	v_max_f32_e32 v5, 0, v5
	v_max_f32_e32 v3, 0, v0
	v_pk_mul_f32 v[4:5], v[4:5], v[4:5]
	v_pk_mul_f32 v[10:11], v[2:3], v[2:3]
	v_lshl_add_u64 v[12:13], v[120:121], 0, s[12:13]
	v_cvt_pk_bf16_f32 v0, v4, v5
	v_cvt_pk_bf16_f32 v1, v6, v7
	v_cvt_pk_bf16_f32 v2, v8, v9
	v_cvt_pk_bf16_f32 v3, v10, v11
	s_and_b64 vcc, exec, s[18:19]
	s_mov_b32 s24, s16
	s_mov_b32 s26, s14
	s_mov_b64 s[30:31], s[22:23]
	s_mov_b64 s[28:29], s[20:21]
	global_store_dwordx4 v[12:13], v[0:3], off offset:256 nt
	s_cbranch_vccz .LBB0_1489
	s_waitcnt vmcnt(0)
	s_cmpk_gt_u32 s2, 0xff
	s_cbranch_scc1 .LBB0_1496
	s_barrier

.LBB0_1561:
	ds_read_b128 v[128:131], v165
	ds_read_b128 v[132:135], v165 offset:1024
	ds_read_b128 v[136:139], v165 offset:2048
	ds_read_b128 v[140:143], v165 offset:3072
	s_add_u32 s26, s24, 0xffe00080
	s_addc_u32 s27, s25, -1
	s_cmpk_eq_i32 s46, 0x7c
	s_cselect_b32 s29, s13, s27
	s_cselect_b32 s28, s42, s26
	s_cselect_b32 s27, s15, s45
	s_cselect_b32 s26, s43, s44
	v_lshl_add_u64 v[160:161], s[24:25], 0, v[152:153]
	s_add_i32 m0, s23, 0xc000
	ds_read_b128 v[144:147], v166
	ds_read_b128 v[156:159], v166 offset:1024
	ds_read_b128 v[168:171], v166 offset:2048
	ds_read_b128 v[172:175], v166 offset:3072
	ds_read_b128 v[176:179], v166 offset:4096
	ds_read_b128 v[180:183], v166 offset:5120
	ds_read_b128 v[184:187], v166 offset:6144
	ds_read_b128 v[188:191], v166 offset:7168
	global_load_lds_dwordx4 v[160:161], off
	v_lshl_add_u64 v[160:161], s[24:25], 0, v[154:155]
	s_add_i32 m0, s23, 0xe000
	s_nop 0
	global_load_lds_dwordx4 v[160:161], off
	s_waitcnt lgkmcnt(8)
	s_barrier
	s_waitcnt lgkmcnt(0)
	s_setprio 1
	s_waitcnt lgkmcnt(0)
	v_mfma_f32_16x16x32_bf16 v[124:127], v[128:131], v[144:147], v[124:127]
	v_mfma_f32_16x16x32_bf16 v[120:123], v[136:139], v[144:147], v[120:123]
	v_mfma_f32_16x16x32_bf16 v[112:115], v[128:131], v[168:171], v[112:115]
	v_mfma_f32_16x16x32_bf16 v[104:107], v[136:139], v[168:171], v[104:107]
	v_mfma_f32_16x16x32_bf16 v[96:99], v[128:131], v[176:179], v[96:99]
	v_mfma_f32_16x16x32_bf16 v[88:91], v[136:139], v[176:179], v[88:91]
	v_mfma_f32_16x16x32_bf16 v[80:83], v[128:131], v[184:187], v[80:83]
	v_mfma_f32_16x16x32_bf16 v[72:75], v[136:139], v[184:187], v[72:75]
	v_mfma_f32_16x16x32_bf16 v[124:127], v[132:135], v[156:159], v[124:127]
	v_mfma_f32_16x16x32_bf16 v[120:123], v[140:143], v[156:159], v[120:123]
	v_mfma_f32_16x16x32_bf16 v[112:115], v[132:135], v[172:175], v[112:115]
	v_mfma_f32_16x16x32_bf16 v[104:107], v[140:143], v[172:175], v[104:107]
	v_mfma_f32_16x16x32_bf16 v[96:99], v[132:135], v[180:183], v[96:99]
	v_mfma_f32_16x16x32_bf16 v[88:91], v[140:143], v[180:183], v[88:91]
	v_mfma_f32_16x16x32_bf16 v[80:83], v[132:135], v[188:191], v[80:83]
	v_mfma_f32_16x16x32_bf16 v[72:75], v[140:143], v[188:191], v[72:75]
	s_setprio 0
	s_barrier
	s_add_i32 s47, s39, s3
	v_lshl_add_u64 v[160:161], s[26:27], 0, v[150:151]
	s_mov_b32 m0, s47
	ds_read_b128 v[192:195], v167
	ds_read_b128 v[196:199], v167 offset:1024
	ds_read_b128 v[200:203], v167 offset:2048
	ds_read_b128 v[204:207], v167 offset:3072
	global_load_lds_dwordx4 v[160:161], off
	v_lshl_add_u64 v[208:209], s[26:27], 0, v[148:149]
	s_add_i32 m0, s47, 0x2000
	s_nop 0
	global_load_lds_dwordx4 v[208:209], off
	s_barrier
	s_waitcnt lgkmcnt(0)
	s_setprio 1
	s_waitcnt lgkmcnt(0)
	v_mfma_f32_16x16x32_bf16 v[116:119], v[192:195], v[144:147], v[116:119]
	v_mfma_f32_16x16x32_bf16 v[108:111], v[200:203], v[144:147], v[108:111]
	v_mfma_f32_16x16x32_bf16 v[100:103], v[192:195], v[168:171], v[100:103]
	v_mfma_f32_16x16x32_bf16 v[92:95], v[200:203], v[168:171], v[92:95]
	v_mfma_f32_16x16x32_bf16 v[84:87], v[192:195], v[176:179], v[84:87]
	v_mfma_f32_16x16x32_bf16 v[76:79], v[200:203], v[176:179], v[76:79]
	v_mfma_f32_16x16x32_bf16 v[68:71], v[192:195], v[184:187], v[68:71]
	v_mfma_f32_16x16x32_bf16 v[64:67], v[200:203], v[184:187], v[64:67]
	v_mfma_f32_16x16x32_bf16 v[116:119], v[196:199], v[156:159], v[116:119]
	v_mfma_f32_16x16x32_bf16 v[108:111], v[204:207], v[156:159], v[108:111]
	v_mfma_f32_16x16x32_bf16 v[100:103], v[196:199], v[172:175], v[100:103]
	v_mfma_f32_16x16x32_bf16 v[92:95], v[204:207], v[172:175], v[92:95]
	v_mfma_f32_16x16x32_bf16 v[84:87], v[196:199], v[180:183], v[84:87]
	v_mfma_f32_16x16x32_bf16 v[76:79], v[204:207], v[180:183], v[76:79]
	v_mfma_f32_16x16x32_bf16 v[68:71], v[196:199], v[188:191], v[68:71]
	v_mfma_f32_16x16x32_bf16 v[64:67], v[204:207], v[188:191], v[64:67]
	s_setprio 0
	s_mov_b32 m0, s23
	v_lshl_add_u64 v[210:211], s[28:29], 0, v[150:151]
	s_barrier
	ds_read_b128 v[144:147], v166 offset:16384
	ds_read_b128 v[156:159], v166 offset:17408
	ds_read_b128 v[168:171], v166 offset:18432
	ds_read_b128 v[172:175], v166 offset:19456
	ds_read_b128 v[176:179], v166 offset:20480
	ds_read_b128 v[180:183], v166 offset:21504
	ds_read_b128 v[184:187], v166 offset:22528
	ds_read_b128 v[188:191], v166 offset:23552
	global_load_lds_dwordx4 v[210:211], off
	v_lshl_add_u64 v[212:213], s[28:29], 0, v[148:149]
	s_mov_b32 m0, s33
	s_nop 0
	global_load_lds_dwordx4 v[212:213], off
	s_barrier
	s_waitcnt lgkmcnt(0)
	s_setprio 1
	s_waitcnt lgkmcnt(0)
	v_mfma_f32_16x16x32_bf16 v[60:63], v[128:131], v[144:147], v[60:63]
	v_mfma_f32_16x16x32_bf16 v[56:59], v[136:139], v[144:147], v[56:59]
	v_mfma_f32_16x16x32_bf16 v[48:51], v[128:131], v[168:171], v[48:51]
	v_mfma_f32_16x16x32_bf16 v[40:43], v[136:139], v[168:171], v[40:43]
	v_mfma_f32_16x16x32_bf16 v[32:35], v[128:131], v[176:179], v[32:35]
	v_mfma_f32_16x16x32_bf16 v[24:27], v[136:139], v[176:179], v[24:27]
	v_mfma_f32_16x16x32_bf16 v[16:19], v[128:131], v[184:187], v[16:19]
	v_mfma_f32_16x16x32_bf16 v[8:11], v[136:139], v[184:187], v[8:11]
	v_mfma_f32_16x16x32_bf16 v[60:63], v[132:135], v[156:159], v[60:63]
	v_mfma_f32_16x16x32_bf16 v[56:59], v[140:143], v[156:159], v[56:59]
	v_mfma_f32_16x16x32_bf16 v[48:51], v[132:135], v[172:175], v[48:51]
	v_mfma_f32_16x16x32_bf16 v[40:43], v[140:143], v[172:175], v[40:43]
	v_mfma_f32_16x16x32_bf16 v[32:35], v[132:135], v[180:183], v[32:35]
	v_mfma_f32_16x16x32_bf16 v[24:27], v[140:143], v[180:183], v[24:27]
	v_mfma_f32_16x16x32_bf16 v[16:19], v[132:135], v[188:191], v[16:19]
	v_mfma_f32_16x16x32_bf16 v[8:11], v[140:143], v[188:191], v[8:11]
	s_setprio 0
	s_barrier
	s_add_u32 s48, s26, 0x200000
	s_addc_u32 s49, s27, 0
	s_add_i32 s47, s40, s3
	v_lshl_add_u64 v[128:129], s[48:49], 0, v[150:151]
	s_mov_b32 m0, s47
	s_nop 0
	global_load_lds_dwordx4 v[128:129], off
	v_lshl_add_u64 v[128:129], s[48:49], 0, v[148:149]
	s_add_i32 m0, s47, 0x2000
	s_nop 0
	global_load_lds_dwordx4 v[128:129], off
	s_waitcnt vmcnt(6)
	s_barrier
	s_setprio 1
	v_mfma_f32_16x16x32_bf16 v[52:55], v[192:195], v[144:147], v[52:55]
	v_mfma_f32_16x16x32_bf16 v[44:47], v[200:203], v[144:147], v[44:47]
	v_mfma_f32_16x16x32_bf16 v[36:39], v[192:195], v[168:171], v[36:39]
	v_mfma_f32_16x16x32_bf16 v[28:31], v[200:203], v[168:171], v[28:31]
	v_mfma_f32_16x16x32_bf16 v[20:23], v[192:195], v[176:179], v[20:23]
	v_mfma_f32_16x16x32_bf16 v[12:15], v[200:203], v[176:179], v[12:15]
	v_mfma_f32_16x16x32_bf16 v[4:7], v[192:195], v[184:187], v[4:7]
	v_mfma_f32_16x16x32_bf16 v[0:3], v[200:203], v[184:187], v[0:3]
	v_mfma_f32_16x16x32_bf16 v[52:55], v[196:199], v[156:159], v[52:55]
	v_mfma_f32_16x16x32_bf16 v[44:47], v[204:207], v[156:159], v[44:47]
	v_mfma_f32_16x16x32_bf16 v[36:39], v[196:199], v[172:175], v[36:39]
	v_mfma_f32_16x16x32_bf16 v[28:31], v[204:207], v[172:175], v[28:31]
	v_mfma_f32_16x16x32_bf16 v[20:23], v[196:199], v[180:183], v[20:23]
	v_mfma_f32_16x16x32_bf16 v[12:15], v[204:207], v[180:183], v[12:15]
	v_mfma_f32_16x16x32_bf16 v[4:7], v[196:199], v[188:191], v[4:7]
	v_mfma_f32_16x16x32_bf16 v[0:3], v[204:207], v[188:191], v[0:3]
	s_setprio 0
	s_add_i32 s47, 16, 0x18000
	v_add_u32_e32 v140, s47, v163
	s_barrier
	ds_read_b128 v[128:131], v140
	ds_read_b128 v[132:135], v140 offset:1024
	ds_read_b128 v[136:139], v140 offset:2048
	ds_read_b128 v[140:143], v140 offset:3072
	s_add_u32 s28, s28, 0x200000
	s_addc_u32 s29, s29, 0
	s_mov_b32 m0, s34
	v_lshl_add_u64 v[192:193], s[28:29], 0, v[150:151]
	ds_read_b128 v[144:147], v166 offset:32768
	ds_read_b128 v[156:159], v166 offset:33792
	ds_read_b128 v[168:171], v166 offset:34816
	ds_read_b128 v[172:175], v166 offset:35840
	ds_read_b128 v[176:179], v166 offset:36864
	ds_read_b128 v[180:183], v166 offset:37888
	ds_read_b128 v[184:187], v166 offset:38912
	ds_read_b128 v[188:191], v166 offset:39936
	global_load_lds_dwordx4 v[192:193], off
	v_lshl_add_u64 v[192:193], s[28:29], 0, v[148:149]
	s_mov_b32 m0, s35
	s_nop 0
	global_load_lds_dwordx4 v[192:193], off
	s_waitcnt lgkmcnt(8)
	s_barrier
	s_waitcnt lgkmcnt(0)
	s_setprio 1
	s_waitcnt lgkmcnt(0)
	v_mfma_f32_16x16x32_bf16 v[124:127], v[128:131], v[144:147], v[124:127]
	v_mfma_f32_16x16x32_bf16 v[120:123], v[136:139], v[144:147], v[120:123]
	v_mfma_f32_16x16x32_bf16 v[112:115], v[128:131], v[168:171], v[112:115]
	v_mfma_f32_16x16x32_bf16 v[104:107], v[136:139], v[168:171], v[104:107]
	v_mfma_f32_16x16x32_bf16 v[96:99], v[128:131], v[176:179], v[96:99]
	v_mfma_f32_16x16x32_bf16 v[88:91], v[136:139], v[176:179], v[88:91]
	v_mfma_f32_16x16x32_bf16 v[80:83], v[128:131], v[184:187], v[80:83]
	v_mfma_f32_16x16x32_bf16 v[72:75], v[136:139], v[184:187], v[72:75]
	v_mfma_f32_16x16x32_bf16 v[124:127], v[132:135], v[156:159], v[124:127]
	v_mfma_f32_16x16x32_bf16 v[120:123], v[140:143], v[156:159], v[120:123]
	v_mfma_f32_16x16x32_bf16 v[112:115], v[132:135], v[172:175], v[112:115]
	v_mfma_f32_16x16x32_bf16 v[104:107], v[140:143], v[172:175], v[104:107]
	v_mfma_f32_16x16x32_bf16 v[96:99], v[132:135], v[180:183], v[96:99]
	v_mfma_f32_16x16x32_bf16 v[88:91], v[140:143], v[180:183], v[88:91]
	v_mfma_f32_16x16x32_bf16 v[80:83], v[132:135], v[188:191], v[80:83]
	v_mfma_f32_16x16x32_bf16 v[72:75], v[140:143], v[188:191], v[72:75]
	s_setprio 0
	s_barrier
	s_add_i32 s28, 16, 0x1c000
	s_add_i32 s29, s47, s3
	v_add_u32_e32 v204, s28, v163
	v_lshl_add_u64 v[160:161], v[160:161], 0, s[6:7]
	s_mov_b32 m0, s29
	ds_read_b128 v[192:195], v204
	ds_read_b128 v[196:199], v204 offset:1024
	ds_read_b128 v[200:203], v204 offset:2048
	ds_read_b128 v[204:207], v204 offset:3072
	global_load_lds_dwordx4 v[160:161], off
	v_lshl_add_u64 v[160:161], v[208:209], 0, s[6:7]
	s_add_i32 m0, s29, 0x2000
	s_nop 0
	global_load_lds_dwordx4 v[160:161], off
	s_barrier
	s_waitcnt lgkmcnt(0)
	s_setprio 1
	s_waitcnt lgkmcnt(0)
	v_mfma_f32_16x16x32_bf16 v[116:119], v[192:195], v[144:147], v[116:119]
	v_mfma_f32_16x16x32_bf16 v[108:111], v[200:203], v[144:147], v[108:111]
	v_mfma_f32_16x16x32_bf16 v[100:103], v[192:195], v[168:171], v[100:103]
	v_mfma_f32_16x16x32_bf16 v[92:95], v[200:203], v[168:171], v[92:95]
	v_mfma_f32_16x16x32_bf16 v[84:87], v[192:195], v[176:179], v[84:87]
	v_mfma_f32_16x16x32_bf16 v[76:79], v[200:203], v[176:179], v[76:79]
	v_mfma_f32_16x16x32_bf16 v[68:71], v[192:195], v[184:187], v[68:71]
	v_mfma_f32_16x16x32_bf16 v[64:67], v[200:203], v[184:187], v[64:67]
	v_mfma_f32_16x16x32_bf16 v[116:119], v[196:199], v[156:159], v[116:119]
	v_mfma_f32_16x16x32_bf16 v[108:111], v[204:207], v[156:159], v[108:111]
	v_mfma_f32_16x16x32_bf16 v[100:103], v[196:199], v[172:175], v[100:103]
	v_mfma_f32_16x16x32_bf16 v[92:95], v[204:207], v[172:175], v[92:95]
	v_mfma_f32_16x16x32_bf16 v[84:87], v[196:199], v[180:183], v[84:87]
	v_mfma_f32_16x16x32_bf16 v[76:79], v[204:207], v[180:183], v[76:79]
	v_mfma_f32_16x16x32_bf16 v[68:71], v[196:199], v[188:191], v[68:71]
	v_mfma_f32_16x16x32_bf16 v[64:67], v[204:207], v[188:191], v[64:67]
	s_setprio 0
	s_mov_b32 m0, s36
	v_lshl_add_u64 v[160:161], v[210:211], 0, s[6:7]
	s_barrier
	ds_read_b128 v[144:147], v166 offset:49152
	ds_read_b128 v[156:159], v166 offset:50176
	ds_read_b128 v[168:171], v166 offset:51200
	ds_read_b128 v[172:175], v166 offset:52224
	ds_read_b128 v[176:179], v166 offset:53248
	ds_read_b128 v[180:183], v166 offset:54272
	ds_read_b128 v[184:187], v166 offset:55296
	ds_read_b128 v[188:191], v166 offset:56320
	global_load_lds_dwordx4 v[160:161], off
	v_lshl_add_u64 v[160:161], v[212:213], 0, s[6:7]
	s_mov_b32 m0, s37
	s_nop 0
	global_load_lds_dwordx4 v[160:161], off
	s_barrier
	s_waitcnt lgkmcnt(0)
	s_setprio 1
	s_waitcnt lgkmcnt(0)
	v_mfma_f32_16x16x32_bf16 v[60:63], v[128:131], v[144:147], v[60:63]
	v_mfma_f32_16x16x32_bf16 v[56:59], v[136:139], v[144:147], v[56:59]
	v_mfma_f32_16x16x32_bf16 v[48:51], v[128:131], v[168:171], v[48:51]
	v_mfma_f32_16x16x32_bf16 v[40:43], v[136:139], v[168:171], v[40:43]
	v_mfma_f32_16x16x32_bf16 v[32:35], v[128:131], v[176:179], v[32:35]
	v_mfma_f32_16x16x32_bf16 v[24:27], v[136:139], v[176:179], v[24:27]
	v_mfma_f32_16x16x32_bf16 v[16:19], v[128:131], v[184:187], v[16:19]
	v_mfma_f32_16x16x32_bf16 v[8:11], v[136:139], v[184:187], v[8:11]
	v_mfma_f32_16x16x32_bf16 v[60:63], v[132:135], v[156:159], v[60:63]
	v_mfma_f32_16x16x32_bf16 v[56:59], v[140:143], v[156:159], v[56:59]
	v_mfma_f32_16x16x32_bf16 v[48:51], v[132:135], v[172:175], v[48:51]
	v_mfma_f32_16x16x32_bf16 v[40:43], v[140:143], v[172:175], v[40:43]
	v_mfma_f32_16x16x32_bf16 v[32:35], v[132:135], v[180:183], v[32:35]
	v_mfma_f32_16x16x32_bf16 v[24:27], v[140:143], v[180:183], v[24:27]
	v_mfma_f32_16x16x32_bf16 v[16:19], v[132:135], v[188:191], v[16:19]
	v_mfma_f32_16x16x32_bf16 v[8:11], v[140:143], v[188:191], v[8:11]
	s_setprio 0
	s_barrier
	s_add_u32 s26, s26, 0x200080
	s_addc_u32 s27, s27, 0
	s_add_i32 s28, s28, s3
	v_lshl_add_u64 v[128:129], s[26:27], 0, v[150:151]
	s_mov_b32 m0, s28
	s_nop 0
	global_load_lds_dwordx4 v[128:129], off
	v_lshl_add_u64 v[128:129], s[26:27], 0, v[148:149]
	s_add_i32 m0, s28, 0x2000
	s_nop 0
	global_load_lds_dwordx4 v[128:129], off
	s_waitcnt vmcnt(6)
	s_barrier
	s_setprio 1
	v_mfma_f32_16x16x32_bf16 v[52:55], v[192:195], v[144:147], v[52:55]
	v_mfma_f32_16x16x32_bf16 v[44:47], v[200:203], v[144:147], v[44:47]
	v_mfma_f32_16x16x32_bf16 v[36:39], v[192:195], v[168:171], v[36:39]
	v_mfma_f32_16x16x32_bf16 v[28:31], v[200:203], v[168:171], v[28:31]
	v_mfma_f32_16x16x32_bf16 v[20:23], v[192:195], v[176:179], v[20:23]
	v_mfma_f32_16x16x32_bf16 v[12:15], v[200:203], v[176:179], v[12:15]
	v_mfma_f32_16x16x32_bf16 v[4:7], v[192:195], v[184:187], v[4:7]
	v_mfma_f32_16x16x32_bf16 v[0:3], v[200:203], v[184:187], v[0:3]
	v_mfma_f32_16x16x32_bf16 v[52:55], v[196:199], v[156:159], v[52:55]
	v_mfma_f32_16x16x32_bf16 v[44:47], v[204:207], v[156:159], v[44:47]
	v_mfma_f32_16x16x32_bf16 v[36:39], v[196:199], v[172:175], v[36:39]
	v_mfma_f32_16x16x32_bf16 v[28:31], v[204:207], v[172:175], v[28:31]
	v_mfma_f32_16x16x32_bf16 v[20:23], v[196:199], v[180:183], v[20:23]
	v_mfma_f32_16x16x32_bf16 v[12:15], v[204:207], v[180:183], v[12:15]
	v_mfma_f32_16x16x32_bf16 v[4:7], v[196:199], v[188:191], v[4:7]
	v_mfma_f32_16x16x32_bf16 v[0:3], v[204:207], v[188:191], v[0:3]
	s_setprio 0
	s_add_i32 s46, s46, 2
	s_add_u32 s24, s24, 0x100
	s_addc_u32 s25, s25, 0
	s_add_u32 s44, s44, 0x100
	s_addc_u32 s45, s45, 0
	s_cmpk_gt_u32 s46, 0x7d
	s_barrier
	s_cbranch_scc0 .LBB0_1561
	s_lshl_b32 s13, s8, 8
	v_add_u32_e32 v158, s13, v162
	s_addk_i32 s13, 0xe000
	s_lshr_b32 s13, s13, 10
	s_mulk_i32 s13, 0x3000
	s_addk_i32 s13, 0x3000
	s_cmp_gt_i32 s8, 31
	s_cselect_b32 s8, s13, 0
	v_lshl_or_b32 v144, s22, 8, v164
	s_lshl_b64 s[24:25], s[8:9], 2
	v_readlane_b32 s26, v253, 2
	v_readlane_b32 s27, v253, 3
	s_add_u32 s24, s26, s24
	v_ashrrev_i32_e32 v145, 31, v144
	s_addc_u32 s25, s27, s25
	v_lshlrev_b64 v[156:157], 2, v[144:145]
	v_ashrrev_i32_e32 v159, 31, v158
	v_lshl_add_u64 v[128:129], s[24:25], 0, v[156:157]
	v_lshlrev_b64 v[146:147], 12, v[158:159]
	v_lshl_add_u64 v[132:133], v[128:129], 0, s[10:11]
	v_add_co_u32_e32 v128, vcc, s38, v128
	v_lshl_add_u64 v[146:147], s[4:5], 0, v[146:147]
	v_lshlrev_b64 v[160:161], 1, v[144:145]
	v_or_b32_e32 v196, 16, v158
	v_addc_co_u32_e32 v129, vcc, 0, v129, vcc
	v_lshl_add_u64 v[144:145], v[146:147], 0, v[160:161]
	v_ashrrev_i32_e32 v197, 31, v196
	global_load_dwordx4 v[140:143], v[128:129], off
	s_nop 0
	global_load_dwordx4 v[128:131], v[132:133], off offset:528
	global_load_dwordx4 v[136:139], v[132:133], off offset:16
	s_nop 0
	global_load_dwordx4 v[132:135], v[132:133], off offset:512
	s_nop 0
	global_load_dwordx4 v[168:171], v[144:145], off
	global_load_dwordx4 v[172:175], v[144:145], off offset:256
	v_lshlrev_b64 v[144:145], 12, v[196:197]
	v_lshl_add_u64 v[144:145], s[4:5], 0, v[144:145]
	v_or_b32_e32 v198, 32, v158
	v_lshl_add_u64 v[144:145], v[144:145], 0, v[160:161]
	v_ashrrev_i32_e32 v199, 31, v198
	global_load_dwordx4 v[176:179], v[144:145], off
	global_load_dwordx4 v[180:183], v[144:145], off offset:256
	v_lshlrev_b64 v[144:145], 12, v[198:199]
	v_lshl_add_u64 v[144:145], s[4:5], 0, v[144:145]
	v_or_b32_e32 v200, 48, v158
	v_lshl_add_u64 v[144:145], v[144:145], 0, v[160:161]
	v_ashrrev_i32_e32 v201, 31, v200
	global_load_dwordx4 v[184:187], v[144:145], off
	global_load_dwordx4 v[188:191], v[144:145], off offset:256
	v_lshlrev_b64 v[144:145], 12, v[200:201]
	v_lshl_add_u64 v[144:145], s[4:5], 0, v[144:145]
	v_lshl_add_u64 v[144:145], v[144:145], 0, v[160:161]
	global_load_dwordx4 v[192:195], v[144:145], off
	s_nop 0
	global_load_dwordx4 v[144:147], v[144:145], off offset:256
	v_lshlrev_b64 v[202:203], 13, v[158:159]
	s_waitcnt vmcnt(0)
	v_lshlrev_b32_e32 v204, 16, v168
	v_and_b32_e32 v205, 0xffff0000, v168
	v_lshlrev_b32_e32 v168, 16, v169
	v_and_b32_e32 v169, 0xffff0000, v169
	v_lshl_add_u64 v[202:203], s[0:1], 0, v[202:203]
	v_lshlrev_b32_e32 v206, 16, v170
	v_and_b32_e32 v207, 0xffff0000, v170
	v_lshlrev_b32_e32 v170, 16, v171
	v_and_b32_e32 v171, 0xffff0000, v171
	v_lshl_add_u64 v[202:203], v[202:203], 0, v[156:157]
	v_pk_fma_f32 v[124:125], v[124:125], v[140:141], v[204:205]
	v_pk_fma_f32 v[126:127], v[126:127], v[142:143], v[168:169]
	global_store_dwordx4 v[202:203], v[124:127], off nt
	v_pk_fma_f32 v[122:123], v[122:123], v[138:139], v[170:171]
	v_pk_fma_f32 v[120:121], v[120:121], v[136:137], v[206:207]
	v_lshlrev_b32_e32 v124, 16, v174
	v_and_b32_e32 v125, 0xffff0000, v174
	v_lshlrev_b32_e32 v126, 16, v175
	v_and_b32_e32 v127, 0xffff0000, v175
	global_store_dwordx4 v[202:203], v[120:123], off offset:16 nt
	v_pk_fma_f32 v[110:111], v[110:111], v[130:131], v[126:127]
	v_pk_fma_f32 v[108:109], v[108:109], v[128:129], v[124:125]
	v_lshlrev_b32_e32 v120, 16, v172
	v_and_b32_e32 v121, 0xffff0000, v172
	v_lshlrev_b32_e32 v122, 16, v173
	v_and_b32_e32 v123, 0xffff0000, v173
	v_pk_fma_f32 v[118:119], v[118:119], v[134:135], v[122:123]
	v_pk_fma_f32 v[116:117], v[116:117], v[132:133], v[120:121]
	global_store_dwordx4 v[202:203], v[108:111], off offset:528 nt
	global_store_dwordx4 v[202:203], v[116:119], off offset:512 nt
	v_lshlrev_b32_e32 v120, 16, v179
	v_lshlrev_b64 v[108:109], 13, v[196:197]
	v_lshlrev_b32_e32 v110, 16, v176
	v_and_b32_e32 v111, 0xffff0000, v176
	v_lshlrev_b32_e32 v116, 16, v177
	v_and_b32_e32 v117, 0xffff0000, v177
	v_lshl_add_u64 v[108:109], s[0:1], 0, v[108:109]
	v_lshlrev_b32_e32 v118, 16, v178
	v_and_b32_e32 v119, 0xffff0000, v178
	v_and_b32_e32 v121, 0xffff0000, v179
	v_lshl_add_u64 v[122:123], v[108:109], 0, v[156:157]
	v_pk_fma_f32 v[108:109], v[112:113], v[140:141], v[110:111]
	v_pk_fma_f32 v[110:111], v[114:115], v[142:143], v[116:117]
	global_store_dwordx4 v[122:123], v[108:111], off nt
	v_pk_fma_f32 v[106:107], v[106:107], v[138:139], v[120:121]
	v_pk_fma_f32 v[104:105], v[104:105], v[136:137], v[118:119]
	v_lshlrev_b32_e32 v108, 16, v182
	v_and_b32_e32 v109, 0xffff0000, v182
	v_lshlrev_b32_e32 v110, 16, v183
	v_and_b32_e32 v111, 0xffff0000, v183
	global_store_dwordx4 v[122:123], v[104:107], off offset:16 nt
	v_pk_fma_f32 v[94:95], v[94:95], v[130:131], v[110:111]
	v_pk_fma_f32 v[92:93], v[92:93], v[128:129], v[108:109]
	v_lshlrev_b32_e32 v104, 16, v180
	v_and_b32_e32 v105, 0xffff0000, v180
	v_lshlrev_b32_e32 v106, 16, v181
	v_and_b32_e32 v107, 0xffff0000, v181
	v_pk_fma_f32 v[102:103], v[102:103], v[134:135], v[106:107]
	v_pk_fma_f32 v[100:101], v[100:101], v[132:133], v[104:105]
	global_store_dwordx4 v[122:123], v[92:95], off offset:528 nt
	global_store_dwordx4 v[122:123], v[100:103], off offset:512 nt
	v_lshlrev_b32_e32 v104, 16, v187
	v_lshlrev_b64 v[92:93], 13, v[198:199]
	v_lshlrev_b32_e32 v94, 16, v184
	v_and_b32_e32 v95, 0xffff0000, v184
	v_lshlrev_b32_e32 v100, 16, v185
	v_and_b32_e32 v101, 0xffff0000, v185
	v_lshl_add_u64 v[92:93], s[0:1], 0, v[92:93]
	v_lshlrev_b32_e32 v102, 16, v186
	v_and_b32_e32 v103, 0xffff0000, v186
	v_and_b32_e32 v105, 0xffff0000, v187
	v_lshl_add_u64 v[106:107], v[92:93], 0, v[156:157]
	v_pk_fma_f32 v[92:93], v[96:97], v[140:141], v[94:95]
	v_pk_fma_f32 v[94:95], v[98:99], v[142:143], v[100:101]
	global_store_dwordx4 v[106:107], v[92:95], off nt
	v_pk_fma_f32 v[90:91], v[90:91], v[138:139], v[104:105]
	v_pk_fma_f32 v[88:89], v[88:89], v[136:137], v[102:103]
	v_lshlrev_b32_e32 v92, 16, v190
	v_and_b32_e32 v93, 0xffff0000, v190
	v_lshlrev_b32_e32 v94, 16, v191
	v_and_b32_e32 v95, 0xffff0000, v191
	global_store_dwordx4 v[106:107], v[88:91], off offset:16 nt
	v_pk_fma_f32 v[78:79], v[78:79], v[130:131], v[94:95]
	v_pk_fma_f32 v[76:77], v[76:77], v[128:129], v[92:93]
	v_lshlrev_b32_e32 v88, 16, v188
	v_and_b32_e32 v89, 0xffff0000, v188
	v_lshlrev_b32_e32 v90, 16, v189
	v_and_b32_e32 v91, 0xffff0000, v189
	v_pk_fma_f32 v[86:87], v[86:87], v[134:135], v[90:91]
	v_pk_fma_f32 v[84:85], v[84:85], v[132:133], v[88:89]
	global_store_dwordx4 v[106:107], v[76:79], off offset:528 nt
	global_store_dwordx4 v[106:107], v[84:87], off offset:512 nt
	v_lshlrev_b32_e32 v88, 16, v195
	v_lshlrev_b64 v[76:77], 13, v[200:201]
	v_lshlrev_b32_e32 v78, 16, v192
	v_and_b32_e32 v79, 0xffff0000, v192
	v_lshlrev_b32_e32 v84, 16, v193
	v_and_b32_e32 v85, 0xffff0000, v193
	v_lshlrev_b32_e32 v86, 16, v194
	v_and_b32_e32 v87, 0xffff0000, v194
	v_and_b32_e32 v89, 0xffff0000, v195
	v_lshl_add_u64 v[76:77], s[0:1], 0, v[76:77]
	v_lshl_add_u64 v[90:91], v[76:77], 0, v[156:157]
	v_pk_fma_f32 v[76:77], v[80:81], v[140:141], v[78:79]
	v_pk_fma_f32 v[78:79], v[82:83], v[142:143], v[84:85]
	v_pk_fma_f32 v[74:75], v[74:75], v[138:139], v[88:89]
	v_pk_fma_f32 v[72:73], v[72:73], v[136:137], v[86:87]
	global_store_dwordx4 v[90:91], v[76:79], off nt
	global_store_dwordx4 v[90:91], v[72:75], off offset:16 nt
	s_nop 0
	v_lshlrev_b32_e32 v76, 16, v146
	v_lshlrev_b32_e32 v72, 16, v144
	v_and_b32_e32 v73, 0xffff0000, v144
	v_lshlrev_b32_e32 v74, 16, v145
	v_and_b32_e32 v75, 0xffff0000, v145
	v_and_b32_e32 v77, 0xffff0000, v146
	v_lshlrev_b32_e32 v78, 16, v147
	v_and_b32_e32 v79, 0xffff0000, v147
	v_pk_fma_f32 v[70:71], v[70:71], v[134:135], v[74:75]
	v_pk_fma_f32 v[68:69], v[68:69], v[132:133], v[72:73]
	v_pk_fma_f32 v[66:67], v[66:67], v[130:131], v[78:79]
	v_pk_fma_f32 v[64:65], v[64:65], v[128:129], v[76:77]
	global_store_dwordx4 v[90:91], v[68:71], off offset:512 nt
	global_store_dwordx4 v[90:91], v[64:67], off offset:528 nt
	v_add_u32_e32 v96, 0x80, v158
	v_ashrrev_i32_e32 v97, 31, v96
	v_lshlrev_b64 v[64:65], 12, v[96:97]
	v_lshl_add_u64 v[64:65], s[4:5], 0, v[64:65]
	v_add_u32_e32 v98, 0x90, v158
	v_lshl_add_u64 v[64:65], v[64:65], 0, v[160:161]
	v_ashrrev_i32_e32 v99, 31, v98
	global_load_dwordx4 v[68:71], v[64:65], off
	global_load_dwordx4 v[72:75], v[64:65], off offset:256
	v_lshlrev_b64 v[64:65], 12, v[98:99]
	v_lshl_add_u64 v[64:65], s[4:5], 0, v[64:65]
	v_add_u32_e32 v100, 0xa0, v158
	v_lshl_add_u64 v[64:65], v[64:65], 0, v[160:161]
	v_ashrrev_i32_e32 v101, 31, v100
	global_load_dwordx4 v[76:79], v[64:65], off
	global_load_dwordx4 v[80:83], v[64:65], off offset:256
	v_lshlrev_b64 v[64:65], 12, v[100:101]
	v_lshl_add_u64 v[64:65], s[4:5], 0, v[64:65]
	v_add_u32_e32 v102, 0xb0, v158
	v_lshl_add_u64 v[64:65], v[64:65], 0, v[160:161]
	v_ashrrev_i32_e32 v103, 31, v102
	global_load_dwordx4 v[84:87], v[64:65], off
	global_load_dwordx4 v[88:91], v[64:65], off offset:256
	v_lshlrev_b64 v[64:65], 12, v[102:103]
	v_lshl_add_u64 v[64:65], s[4:5], 0, v[64:65]
	v_lshl_add_u64 v[64:65], v[64:65], 0, v[160:161]
	global_load_dwordx4 v[92:95], v[64:65], off
	s_nop 0
	global_load_dwordx4 v[64:67], v[64:65], off offset:256
	v_lshlrev_b64 v[96:97], 13, v[96:97]
	s_waitcnt vmcnt(0)
	v_lshlrev_b32_e32 v104, 16, v68
	v_and_b32_e32 v105, 0xffff0000, v68
	v_lshlrev_b32_e32 v68, 16, v69
	v_and_b32_e32 v69, 0xffff0000, v69
	v_lshl_add_u64 v[96:97], s[0:1], 0, v[96:97]
	v_lshlrev_b32_e32 v106, 16, v70
	v_and_b32_e32 v107, 0xffff0000, v70
	v_lshlrev_b32_e32 v70, 16, v71
	v_and_b32_e32 v71, 0xffff0000, v71
	v_lshl_add_u64 v[96:97], v[96:97], 0, v[156:157]
	v_pk_fma_f32 v[62:63], v[62:63], v[142:143], v[68:69]
	v_pk_fma_f32 v[60:61], v[60:61], v[140:141], v[104:105]
	global_store_dwordx4 v[96:97], v[60:63], off nt
	v_pk_fma_f32 v[58:59], v[58:59], v[138:139], v[70:71]
	v_pk_fma_f32 v[56:57], v[56:57], v[136:137], v[106:107]
	v_lshlrev_b32_e32 v60, 16, v74
	v_and_b32_e32 v61, 0xffff0000, v74
	v_lshlrev_b32_e32 v62, 16, v75
	v_and_b32_e32 v63, 0xffff0000, v75
	global_store_dwordx4 v[96:97], v[56:59], off offset:16 nt
	v_pk_fma_f32 v[46:47], v[46:47], v[130:131], v[62:63]
	v_pk_fma_f32 v[44:45], v[44:45], v[128:129], v[60:61]
	v_lshlrev_b32_e32 v56, 16, v72
	v_and_b32_e32 v57, 0xffff0000, v72
	v_lshlrev_b32_e32 v58, 16, v73
	v_and_b32_e32 v59, 0xffff0000, v73
	v_pk_fma_f32 v[54:55], v[54:55], v[134:135], v[58:59]
	v_pk_fma_f32 v[52:53], v[52:53], v[132:133], v[56:57]
	global_store_dwordx4 v[96:97], v[44:47], off offset:528 nt
	global_store_dwordx4 v[96:97], v[52:55], off offset:512 nt
	v_lshlrev_b32_e32 v56, 16, v79
	v_lshlrev_b64 v[44:45], 13, v[98:99]
	v_lshlrev_b32_e32 v52, 16, v76
	v_and_b32_e32 v53, 0xffff0000, v76
	v_lshlrev_b32_e32 v46, 16, v77
	v_and_b32_e32 v47, 0xffff0000, v77
	v_lshl_add_u64 v[44:45], s[0:1], 0, v[44:45]
	v_lshlrev_b32_e32 v54, 16, v78
	v_and_b32_e32 v55, 0xffff0000, v78
	v_and_b32_e32 v57, 0xffff0000, v79
	v_lshl_add_u64 v[58:59], v[44:45], 0, v[156:157]
	v_pk_fma_f32 v[46:47], v[50:51], v[142:143], v[46:47]
	v_pk_fma_f32 v[44:45], v[48:49], v[140:141], v[52:53]
	global_store_dwordx4 v[58:59], v[44:47], off nt
	v_pk_fma_f32 v[42:43], v[42:43], v[138:139], v[56:57]
	v_pk_fma_f32 v[40:41], v[40:41], v[136:137], v[54:55]
	v_lshlrev_b32_e32 v44, 16, v82
	v_and_b32_e32 v45, 0xffff0000, v82
	v_lshlrev_b32_e32 v46, 16, v83
	v_and_b32_e32 v47, 0xffff0000, v83
	global_store_dwordx4 v[58:59], v[40:43], off offset:16 nt
	v_pk_fma_f32 v[30:31], v[30:31], v[130:131], v[46:47]
	v_pk_fma_f32 v[28:29], v[28:29], v[128:129], v[44:45]
	v_lshlrev_b32_e32 v40, 16, v80
	v_and_b32_e32 v41, 0xffff0000, v80
	v_lshlrev_b32_e32 v42, 16, v81
	v_and_b32_e32 v43, 0xffff0000, v81
	v_pk_fma_f32 v[38:39], v[38:39], v[134:135], v[42:43]
	v_pk_fma_f32 v[36:37], v[36:37], v[132:133], v[40:41]
	global_store_dwordx4 v[58:59], v[28:31], off offset:528 nt
	global_store_dwordx4 v[58:59], v[36:39], off offset:512 nt
	v_lshlrev_b32_e32 v40, 16, v87
	v_lshlrev_b64 v[28:29], 13, v[100:101]
	v_lshlrev_b32_e32 v36, 16, v84
	v_and_b32_e32 v37, 0xffff0000, v84
	v_lshlrev_b32_e32 v30, 16, v85
	v_and_b32_e32 v31, 0xffff0000, v85
	v_lshl_add_u64 v[28:29], s[0:1], 0, v[28:29]
	v_lshlrev_b32_e32 v38, 16, v86
	v_and_b32_e32 v39, 0xffff0000, v86
	v_and_b32_e32 v41, 0xffff0000, v87
	v_lshl_add_u64 v[42:43], v[28:29], 0, v[156:157]
	v_pk_fma_f32 v[30:31], v[34:35], v[142:143], v[30:31]
	v_pk_fma_f32 v[28:29], v[32:33], v[140:141], v[36:37]
	global_store_dwordx4 v[42:43], v[28:31], off nt
	v_pk_fma_f32 v[26:27], v[26:27], v[138:139], v[40:41]
	v_pk_fma_f32 v[24:25], v[24:25], v[136:137], v[38:39]
	v_lshlrev_b32_e32 v28, 16, v90
	v_and_b32_e32 v29, 0xffff0000, v90
	v_lshlrev_b32_e32 v30, 16, v91
	v_and_b32_e32 v31, 0xffff0000, v91
	global_store_dwordx4 v[42:43], v[24:27], off offset:16 nt
	v_pk_fma_f32 v[14:15], v[14:15], v[130:131], v[30:31]
	v_pk_fma_f32 v[12:13], v[12:13], v[128:129], v[28:29]
	v_lshlrev_b32_e32 v24, 16, v88
	v_and_b32_e32 v25, 0xffff0000, v88
	v_lshlrev_b32_e32 v26, 16, v89
	v_and_b32_e32 v27, 0xffff0000, v89
	v_pk_fma_f32 v[22:23], v[22:23], v[134:135], v[26:27]
	v_pk_fma_f32 v[20:21], v[20:21], v[132:133], v[24:25]
	global_store_dwordx4 v[42:43], v[12:15], off offset:528 nt
	global_store_dwordx4 v[42:43], v[20:23], off offset:512 nt
	v_lshlrev_b32_e32 v24, 16, v95
	v_lshlrev_b64 v[12:13], 13, v[102:103]
	v_lshlrev_b32_e32 v20, 16, v92
	v_and_b32_e32 v21, 0xffff0000, v92
	v_lshlrev_b32_e32 v14, 16, v93
	v_and_b32_e32 v15, 0xffff0000, v93
	v_lshlrev_b32_e32 v22, 16, v94
	v_and_b32_e32 v23, 0xffff0000, v94
	v_and_b32_e32 v25, 0xffff0000, v95
	v_lshl_add_u64 v[12:13], s[0:1], 0, v[12:13]
	v_lshl_add_u64 v[26:27], v[12:13], 0, v[156:157]
	v_pk_fma_f32 v[14:15], v[18:19], v[142:143], v[14:15]
	v_pk_fma_f32 v[12:13], v[16:17], v[140:141], v[20:21]
	v_pk_fma_f32 v[10:11], v[10:11], v[138:139], v[24:25]
	v_pk_fma_f32 v[8:9], v[8:9], v[136:137], v[22:23]
	global_store_dwordx4 v[26:27], v[12:15], off nt
	global_store_dwordx4 v[26:27], v[8:11], off offset:16 nt
	s_nop 0
	v_lshlrev_b32_e32 v12, 16, v66
	v_lshlrev_b32_e32 v8, 16, v64
	v_and_b32_e32 v9, 0xffff0000, v64
	v_lshlrev_b32_e32 v10, 16, v65
	v_and_b32_e32 v11, 0xffff0000, v65
	v_and_b32_e32 v13, 0xffff0000, v66
	v_lshlrev_b32_e32 v14, 16, v67
	v_and_b32_e32 v15, 0xffff0000, v67
	v_pk_fma_f32 v[6:7], v[6:7], v[134:135], v[10:11]
	v_pk_fma_f32 v[4:5], v[4:5], v[132:133], v[8:9]
	v_pk_fma_f32 v[2:3], v[2:3], v[130:131], v[14:15]
	v_pk_fma_f32 v[0:1], v[0:1], v[128:129], v[12:13]
	global_store_dwordx4 v[26:27], v[4:7], off offset:512 nt
	global_store_dwordx4 v[26:27], v[0:3], off offset:528 nt
	s_and_b64 vcc, exec, s[16:17]
	s_mov_b32 s22, s14
	s_mov_b32 s8, s12
	s_mov_b64 s[26:27], s[20:21]
	s_mov_b64 s[24:25], s[18:19]
	s_cbranch_vccz .LBB0_1558
	s_waitcnt vmcnt(0)
	s_cmpk_gt_u32 s2, 0xff
	s_cbranch_scc1 .LBB0_1565
	s_barrier
